# v29 with one s_nop after the P1 gate GEMM: downstream loops back at the baseline's 8-byte phase (placement check)
# speedup vs baseline: 1.0067x; 1.0067x over previous
.LBB0_218:
	s_add_i32 s0, s20, 0xfffff000
	s_lshr_b32 s1, s0, 11
	s_mulk_i32 s1, 0x3000
	s_add_i32 s4, s1, 0x3000
	s_cmpk_lt_i32 s20, 0x1000
	s_cselect_b32 s1, s21, 0
	s_cselect_b32 s0, s20, s0
	s_cselect_b32 s33, s37, s39
	s_cselect_b32 s62, s36, s38
	s_cselect_b32 s4, 0, s4
	s_lshl_b64 s[0:1], s[0:1], 13
	s_add_u32 s0, s62, s0
	s_addc_u32 s1, s33, s1
	s_lshl_b64 s[62:63], s[4:5], 2
	s_add_u32 s62, s10, s62
	s_addc_u32 s63, s11, s63
	s_add_u32 s68, s62, 0x2000
	v_lshl_add_u64 v[24:25], s[0:1], 0, v[110:111]
	s_addc_u32 s69, s63, 0
	global_load_dwordx4 v[44:47], v110, s[0:1]
	global_load_dwordx4 v[52:55], v110, s[0:1] offset:1024
	global_load_dwordx4 v[20:23], v[116:117], off
	global_load_dwordx4 v[16:19], v[116:117], off offset:1024
	global_load_dwordx4 v[162:165], v129, s[68:69]
	global_load_dwordx4 v[170:173], v183, s[68:69]
	global_load_dwordx4 v[4:7], v129, s[62:63]
	global_load_dwordx4 v[0:3], v129, s[62:63] offset:1024
	global_load_dwordx4 v[56:59], v110, s[0:1] offset:2048
	global_load_dwordx4 v[64:67], v110, s[0:1] offset:3072
	global_load_dwordx4 v[36:39], v[116:117], off offset:2048
	global_load_dwordx4 v[32:35], v[116:117], off offset:3072
	global_load_dwordx4 v[174:177], v186, s[68:69]
	global_load_dwordx4 v[198:201], v187, s[68:69]
	global_load_dwordx4 v[12:15], v129, s[62:63] offset:2048
	global_load_dwordx4 v[8:11], v129, s[62:63] offset:3072
	s_movk_i32 s0, 0x1000
	v_add_co_u32_e64 v48, s[0:1], s0, v24
	s_nop 1
	v_addc_co_u32_e64 v49, s[0:1], 0, v25, s[0:1]
	global_load_dwordx4 v[202:205], v188, s[68:69]
	global_load_dwordx4 v[24:27], v188, s[62:63]
	global_load_dwordx4 v[84:87], v[48:49], off
	global_load_dwordx4 v[80:83], v[48:49], off offset:1024
	global_load_dwordx4 v[68:71], v[118:119], off
	global_load_dwordx4 v[60:63], v[120:121], off
	global_load_dwordx4 v[104:107], v189, s[68:69]
	global_load_dwordx4 v[28:31], v189, s[62:63]
	global_load_dwordx4 v[100:103], v190, s[68:69]
	global_load_dwordx4 v[40:43], v190, s[62:63]
	global_load_dwordx4 v[92:95], v[48:49], off offset:2048
	global_load_dwordx4 v[88:91], v[48:49], off offset:3072
	global_load_dwordx4 v[76:79], v[122:123], off
	global_load_dwordx4 v[72:75], v[124:125], off
	global_load_dwordx4 v[96:99], v191, s[68:69]
	s_nop 0
	global_load_dwordx4 v[48:51], v191, s[62:63]
	s_waitcnt vmcnt(31)
	v_mov_b32_e32 v142, v45
	s_waitcnt vmcnt(30)
	v_mov_b32_e32 v143, v53
	v_mov_b32_e32 v146, v47
	v_mov_b32_e32 v147, v55
	v_mov_b32_e32 v138, v44
	v_mov_b32_e32 v139, v52
	v_mov_b32_e32 v140, v46
	v_mov_b32_e32 v141, v54
	s_waitcnt vmcnt(23)
	v_pk_mul_f32 v[148:149], v[58:59], v[58:59]
	v_pk_mul_f32 v[144:145], v[56:57], v[56:57]
	v_pk_mul_f32 v[142:143], v[142:143], v[142:143]
	v_pk_mul_f32 v[146:147], v[146:147], v[146:147]
	v_pk_add_f32 v[152:153], v[162:163], 1.0 op_sel_hi:[1,0]
	v_pk_add_f32 v[162:163], v[172:173], 1.0 op_sel_hi:[1,0]
	s_waitcnt vmcnt(19)
	v_pk_add_f32 v[172:173], v[174:175], 1.0 op_sel_hi:[1,0]
	s_waitcnt vmcnt(18)
	v_pk_add_f32 v[174:175], v[200:201], 1.0 op_sel_hi:[1,0]
	s_waitcnt vmcnt(15)
	v_pk_add_f32 v[200:201], v[202:203], 1.0 op_sel_hi:[1,0]
	v_pk_mov_b32 v[202:203], v[144:145], v[148:149] op_sel:[1,0]
	v_mov_b32_e32 v145, v149
	v_pk_fma_f32 v[138:139], v[138:139], v[138:139], v[142:143]
	v_pk_fma_f32 v[140:141], v[140:141], v[140:141], v[146:147]
	v_mul_f32_e32 v156, v65, v65
	v_mul_f32_e32 v158, v67, v67
	v_pk_add_f32 v[142:143], v[202:203], v[144:145]
	v_pk_add_f32 v[138:139], v[138:139], v[140:141]
	s_waitcnt vmcnt(13)
	v_mul_f32_e32 v133, v84, v84
	v_mul_f32_e32 v210, v85, v85
	v_mul_f32_e32 v211, v86, v86
	v_mul_f32_e32 v212, v87, v87
	v_pk_add_f32 v[150:151], v[164:165], 1.0 op_sel_hi:[1,0]
	v_pk_add_f32 v[164:165], v[170:171], 1.0 op_sel_hi:[1,0]
	v_pk_add_f32 v[170:171], v[176:177], 1.0 op_sel_hi:[1,0]
	v_pk_add_f32 v[176:177], v[198:199], 1.0 op_sel_hi:[1,0]
	v_pk_add_f32 v[198:199], v[204:205], 1.0 op_sel_hi:[1,0]
	v_pk_fma_f32 v[148:149], v[64:65], v[64:65], v[156:157] op_sel_hi:[1,1,0]
	v_pk_fma_f32 v[204:205], v[66:67], v[66:67], v[158:159] op_sel_hi:[1,1,0]
	v_pk_add_f32 v[140:141], v[142:143], v[142:143] op_sel:[0,1] op_sel_hi:[1,0]
	v_pk_add_f32 v[138:139], v[138:139], v[138:139] op_sel:[0,1] op_sel_hi:[1,0]
	s_waitcnt vmcnt(12)
	v_pk_mul_f32 v[160:161], v[82:83], v[82:83]
	v_pk_mul_f32 v[154:155], v[80:81], v[80:81]
	v_mov_b32_e32 v149, v211
	v_mov_b32_e32 v205, v212
	v_mov_b32_e32 v141, v210
	v_mov_b32_e32 v139, v133
	v_pk_mov_b32 v[206:207], v[154:155], v[160:161] op_sel:[1,0]
	v_mov_b32_e32 v155, v161
	v_pk_add_f32 v[142:143], v[148:149], v[204:205]
	v_pk_add_f32 v[138:139], v[138:139], v[140:141]
	s_waitcnt vmcnt(5)
	v_mul_f32_e32 v166, v93, v93
	v_mul_f32_e32 v168, v95, v95
	v_pk_add_f32 v[144:145], v[206:207], v[154:155]
	v_pk_add_f32 v[138:139], v[138:139], v[142:143]
	s_waitcnt vmcnt(4)
	v_mul_f32_e32 v213, v88, v88
	v_mul_f32_e32 v214, v89, v89
	v_mul_f32_e32 v215, v90, v90
	v_mul_f32_e32 v216, v91, v91
	v_pk_fma_f32 v[160:161], v[92:93], v[92:93], v[166:167] op_sel_hi:[1,1,0]
	v_pk_fma_f32 v[208:209], v[94:95], v[94:95], v[168:169] op_sel_hi:[1,1,0]
	v_pk_add_f32 v[144:145], v[144:145], v[144:145] op_sel:[0,1] op_sel_hi:[1,0]
	v_pk_add_f32 v[138:139], v[138:139], v[138:139] op_sel:[0,1] op_sel_hi:[1,0]
	v_mov_b32_e32 v161, v215
	v_mov_b32_e32 v209, v216
	v_mov_b32_e32 v145, v214
	v_mov_b32_e32 v139, v213
	v_pk_add_f32 v[146:147], v[160:161], v[208:209]
	v_pk_add_f32 v[138:139], v[138:139], v[144:145]
	v_lshl_add_u64 v[178:179], s[28:29], 0, v[136:137]
	v_pk_add_f32 v[138:139], v[138:139], v[146:147]
	v_add_co_u32_e64 v178, s[0:1], s16, v178
	v_add_f32_e32 v133, v138, v139
	ds_bpermute_b32 v138, v109, v133
	v_lshl_add_u64 v[180:181], s[28:29], 0, v[134:135]
	v_addc_co_u32_e64 v179, s[0:1], 0, v179, s[0:1]
	v_add_co_u32_e64 v180, s[0:1], s17, v180
	s_waitcnt lgkmcnt(0)
	v_add_f32_e32 v133, v133, v138
	ds_bpermute_b32 v138, v113, v133
	s_mov_b32 s4, 0x800000
	v_addc_co_u32_e64 v181, s[0:1], 0, v181, s[0:1]
	v_mov_b32_e32 v218, v111
	s_waitcnt lgkmcnt(0)
	v_add_f32_e32 v133, v133, v138
	ds_bpermute_b32 v138, v115, v133
	v_mov_b32_e32 v219, v111
	v_pk_add_f32 v[106:107], v[106:107], 1.0 op_sel_hi:[1,0]
	v_pk_add_f32 v[104:105], v[104:105], 1.0 op_sel_hi:[1,0]
	v_pk_add_f32 v[100:101], v[100:101], 1.0 op_sel_hi:[1,0]
	s_waitcnt lgkmcnt(0)
	v_add_f32_e32 v133, v133, v138
	ds_bpermute_b32 v138, v157, v133
	s_waitcnt vmcnt(1)
	v_pk_add_f32 v[96:97], v[96:97], 1.0 op_sel_hi:[1,0]
	v_mov_b32_e32 v220, v111
	v_mov_b32_e32 v221, v111
	v_mov_b32_e32 v222, v111
	s_waitcnt lgkmcnt(0)
	v_add_f32_e32 v133, v133, v138
	ds_bpermute_b32 v138, v159, v133
	v_mov_b32_e32 v223, v111
	v_mov_b32_e32 v224, v111
	v_mov_b32_e32 v225, v111
	v_add_u32_e32 v217, s7, v169
	s_waitcnt lgkmcnt(0)
	v_add_f32_e32 v133, v133, v138
	ds_bpermute_b32 v138, v167, v133
	s_addk_i32 s7, 0x1010
	s_add_u32 s20, s20, 1
	v_pk_add_f32 v[102:103], v[102:103], 1.0 op_sel_hi:[1,0]
	v_pk_add_f32 v[98:99], v[98:99], 1.0 op_sel_hi:[1,0]
	s_waitcnt lgkmcnt(0)
	v_add_f32_e32 v133, v133, v138
	v_fmamk_f32 v133, v133, 0x3a000000, v192
	v_mul_f32_e32 v138, 0x4b800000, v133
	v_cmp_gt_f32_e64 s[0:1], s4, v133
	s_addc_u32 s21, s21, 0
	v_lshl_add_u64 v[134:135], v[134:135], 0, s[8:9]
	v_cndmask_b32_e64 v133, v133, v138, s[0:1]
	v_rsq_f32_e32 v133, v133
	v_lshl_add_u64 v[136:137], v[136:137], 0, s[12:13]
	s_cmpk_eq_i32 s7, 0x4040
	v_mul_f32_e32 v138, 0x45800000, v133
	v_cndmask_b32_e64 v138, v133, v138, s[0:1]
	v_pk_mul_f32 v[44:45], v[44:45], v[138:139] op_sel_hi:[1,0]
	v_pk_mul_f32 v[52:53], v[52:53], v[138:139] op_sel_hi:[1,0]
	v_pk_mul_f32 v[20:21], v[20:21], v[44:45]
	v_pk_mul_f32 v[16:17], v[16:17], v[52:53]
	v_pk_fma_f32 v[4:5], v[152:153], v[20:21], v[4:5]
	v_pk_mul_f32 v[46:47], v[46:47], v[138:139] op_sel_hi:[1,0]
	v_cvt_pk_fp8_f32 v218, v4, v5
	v_pk_mul_f32 v[54:55], v[54:55], v[138:139] op_sel_hi:[1,0]
	v_pk_mul_f32 v[56:57], v[56:57], v[138:139] op_sel_hi:[1,0]
	v_pk_mul_f32 v[64:65], v[64:65], v[138:139] op_sel_hi:[1,0]
	v_pk_mul_f32 v[86:87], v[86:87], v[138:139] op_sel_hi:[1,0]
	v_pk_mul_f32 v[84:85], v[84:85], v[138:139] op_sel_hi:[1,0]
	v_pk_mul_f32 v[82:83], v[82:83], v[138:139] op_sel_hi:[1,0]
	v_pk_mul_f32 v[80:81], v[80:81], v[138:139] op_sel_hi:[1,0]
	v_pk_mul_f32 v[92:93], v[92:93], v[138:139] op_sel_hi:[1,0]
	v_pk_mul_f32 v[88:89], v[88:89], v[138:139] op_sel_hi:[1,0]
	v_pk_fma_f32 v[0:1], v[164:165], v[16:17], v[0:1]
	v_pk_mul_f32 v[22:23], v[22:23], v[46:47]
	v_pk_mul_f32 v[18:19], v[18:19], v[54:55]
	v_pk_mul_f32 v[36:37], v[36:37], v[56:57]
	v_pk_mul_f32 v[32:33], v[32:33], v[64:65]
	v_pk_mul_f32 v[44:45], v[68:69], v[84:85]
	v_pk_mul_f32 v[46:47], v[70:71], v[86:87]
	v_pk_mul_f32 v[52:53], v[60:61], v[80:81]
	v_pk_mul_f32 v[54:55], v[62:63], v[82:83]
	v_pk_mul_f32 v[56:57], v[76:77], v[92:93]
	v_pk_mul_f32 v[60:61], v[72:73], v[88:89]
	v_cvt_pk_fp8_f32 v219, v0, v1
	v_pk_fma_f32 v[6:7], v[150:151], v[22:23], v[6:7]
	v_pk_fma_f32 v[2:3], v[162:163], v[18:19], v[2:3]
	v_pk_fma_f32 v[12:13], v[172:173], v[36:37], v[12:13]
	v_pk_fma_f32 v[8:9], v[176:177], v[32:33], v[8:9]
	v_pk_fma_f32 v[16:17], v[198:199], v[46:47], v[26:27]
	v_pk_fma_f32 v[18:19], v[200:201], v[44:45], v[24:25]
	v_pk_fma_f32 v[20:21], v[106:107], v[54:55], v[30:31]
	v_pk_fma_f32 v[22:23], v[104:105], v[52:53], v[28:29]
	v_pk_fma_f32 v[26:27], v[100:101], v[56:57], v[40:41]
	s_waitcnt vmcnt(0)
	v_pk_fma_f32 v[30:31], v[96:97], v[60:61], v[48:49]
	v_cvt_pk_fp8_f32 v220, v12, v13
	v_cvt_pk_fp8_f32 v221, v8, v9
	v_cvt_pk_fp8_f32 v222, v18, v19
	v_cvt_pk_fp8_f32 v223, v22, v23
	v_cvt_pk_fp8_f32 v224, v26, v27
	v_cvt_pk_fp8_f32 v225, v30, v31
	v_cvt_pk_fp8_f32 v218, v6, v7 op_sel:[0,0,1]
	v_pk_mul_f32 v[58:59], v[58:59], v[138:139] op_sel_hi:[1,0]
	v_pk_mul_f32 v[66:67], v[66:67], v[138:139] op_sel_hi:[1,0]
	v_pk_mul_f32 v[94:95], v[94:95], v[138:139] op_sel_hi:[1,0]
	v_pk_mul_f32 v[90:91], v[90:91], v[138:139] op_sel_hi:[1,0]
	v_pk_mul_f32 v[38:39], v[38:39], v[58:59]
	v_pk_mul_f32 v[34:35], v[34:35], v[66:67]
	v_pk_mul_f32 v[58:59], v[78:79], v[94:95]
	v_pk_mul_f32 v[62:63], v[74:75], v[90:91]
	v_cvt_pk_fp8_f32 v219, v2, v3 op_sel:[0,0,1]
	v_pk_fma_f32 v[14:15], v[170:171], v[38:39], v[14:15]
	v_pk_fma_f32 v[10:11], v[174:175], v[34:35], v[10:11]
	v_pk_fma_f32 v[24:25], v[102:103], v[58:59], v[42:43]
	v_pk_fma_f32 v[28:29], v[98:99], v[62:63], v[50:51]
	v_cvt_pk_bf16_f32 v32, v4, v5
	v_cvt_pk_bf16_f32 v33, v6, v7
	v_cvt_pk_bf16_f32 v4, v0, v1
	v_cvt_pk_bf16_f32 v5, v2, v3
	v_cvt_pk_bf16_f32 v0, v12, v13
	v_cvt_pk_bf16_f32 v1, v14, v15
	v_cvt_pk_bf16_f32 v12, v8, v9
	v_cvt_pk_bf16_f32 v13, v10, v11
	v_cvt_pk_bf16_f32 v8, v18, v19
	v_cvt_pk_bf16_f32 v9, v16, v17
	v_cvt_pk_bf16_f32 v18, v22, v23
	v_cvt_pk_bf16_f32 v19, v20, v21
	v_cvt_pk_bf16_f32 v22, v26, v27
	v_cvt_pk_bf16_f32 v23, v24, v25
	v_cvt_pk_bf16_f32 v26, v30, v31
	v_cvt_pk_bf16_f32 v27, v28, v29
	global_store_dwordx2 v[178:179], v[32:33], off sc1
	ds_write2st64_b64 v217, v[32:33], v[4:5] offset1:1
	ds_write2st64_b64 v217, v[0:1], v[12:13] offset0:2 offset1:3
	ds_write2st64_b64 v217, v[8:9], v[18:19] offset0:4 offset1:5
	ds_write2st64_b64 v217, v[22:23], v[26:27] offset0:6 offset1:7
	v_cvt_pk_fp8_f32 v220, v14, v15 op_sel:[0,0,1]
	v_cvt_pk_fp8_f32 v221, v10, v11 op_sel:[0,0,1]
	v_cvt_pk_fp8_f32 v222, v16, v17 op_sel:[0,0,1]
	v_cvt_pk_fp8_f32 v223, v20, v21 op_sel:[0,0,1]
	v_cvt_pk_fp8_f32 v224, v24, v25 op_sel:[0,0,1]
	v_cvt_pk_fp8_f32 v225, v28, v29 op_sel:[0,0,1]
	global_store_dword v[180:181], v218, off sc1
	global_store_dwordx2 v[178:179], v[4:5], off offset:512 sc1
	global_store_dword v[180:181], v219, off offset:256 sc1
	global_store_dwordx2 v[178:179], v[0:1], off offset:1024 sc1
	global_store_dword v[180:181], v220, off offset:512 sc1
	global_store_dwordx2 v[178:179], v[12:13], off offset:1536 sc1
	global_store_dword v[180:181], v221, off offset:768 sc1
	global_store_dwordx2 v[178:179], v[8:9], off offset:2048 sc1
	global_store_dword v[180:181], v222, off offset:1024 sc1
	global_store_dwordx2 v[178:179], v[18:19], off offset:2560 sc1
	global_store_dword v[180:181], v223, off offset:1280 sc1
	global_store_dwordx2 v[178:179], v[22:23], off offset:3072 sc1
	global_store_dword v[180:181], v224, off offset:1536 sc1
	global_store_dwordx2 v[178:179], v[26:27], off offset:3584 sc1
	global_store_dword v[180:181], v225, off offset:1792 sc1
	s_cbranch_scc0 .LBB0_218
	v_mov_b32_e32 v0, 0
	v_mov_b32_e32 v1, v0
	v_mov_b32_e32 v2, v0
	v_mov_b32_e32 v3, v0
	v_mov_b32_e32 v12, v0
	v_mov_b32_e32 v13, v0
	v_mov_b32_e32 v14, v0
	v_mov_b32_e32 v15, v0
	v_mov_b32_e32 v8, v0
	v_mov_b32_e32 v9, v0
	v_mov_b32_e32 v10, v0
	v_mov_b32_e32 v11, v0
	v_mov_b32_e32 v16, v0
	v_mov_b32_e32 v17, v0
	v_mov_b32_e32 v18, v0
	v_mov_b32_e32 v19, v0
	v_mov_b32_e32 v4, v0
	v_mov_b32_e32 v5, v0
	v_mov_b32_e32 v6, v0
	v_mov_b32_e32 v7, v0
	v_mov_b32_e32 v20, v0
	v_mov_b32_e32 v21, v0
	v_mov_b32_e32 v22, v0
	v_mov_b32_e32 v23, v0
	v_mov_b32_e32 v148, v128
	v_ashrrev_i32_e32 v149, 31, v128
	v_lshl_add_u64 v[148:149], v[148:149], 1, v[126:127]
	s_mov_b64 s[0:1], 0x10000
	v_add_u32_e32 v150, 0x10100, v182
	v_lshl_add_u64 v[164:165], v[148:149], 0, s[0:1]
	s_mov_b64 s[0:1], 0x20000
	v_lshl_add_u64 v[170:171], v[148:149], 0, s[0:1]
	global_load_dwordx4 v[28:31], v[148:149], off
	global_load_dwordx4 v[32:35], v[164:165], off
	global_load_dwordx4 v[36:39], v[170:171], off
	global_load_dwordx4 v[40:43], v[148:149], off offset:64
	global_load_dwordx4 v[44:47], v[164:165], off offset:64
	global_load_dwordx4 v[48:51], v[170:171], off offset:64
	global_load_dwordx4 v[136:139], v[148:149], off offset:128
	global_load_dwordx4 v[140:143], v[164:165], off offset:128
	global_load_dwordx4 v[144:147], v[170:171], off offset:128
	global_load_dwordx4 v[160:163], v[148:149], off offset:192
	global_load_dwordx4 v[198:201], v[164:165], off offset:192
	global_load_dwordx4 v[202:205], v[170:171], off offset:192
	global_load_dwordx4 v[206:209], v[148:149], off offset:256
	global_load_dwordx4 v[210:213], v[164:165], off offset:256
	global_load_dwordx4 v[214:217], v[170:171], off offset:256
	global_load_dwordx4 v[218:221], v[148:149], off offset:320
	global_load_dwordx4 v[222:225], v[164:165], off offset:320
	global_load_dwordx4 v[226:229], v[170:171], off offset:320
	global_load_dwordx4 v[230:233], v[148:149], off offset:384
	global_load_dwordx4 v[234:237], v[164:165], off offset:384
	global_load_dwordx4 v[238:241], v[170:171], off offset:384
	s_waitcnt lgkmcnt(0)
	s_barrier
	ds_read_b128 v[24:27], v182
	ds_read_b128 v[152:155], v150
	ds_read_b128 v[178:181], v182 offset:64
	ds_read_b128 v[246:249], v150 offset:64
	s_waitcnt vmcnt(18) lgkmcnt(2)
	v_mfma_f32_16x16x32_bf16 v[0:3], v[24:27], v[28:31], v[0:3]
	v_mfma_f32_16x16x32_bf16 v[16:19], v[152:155], v[28:31], v[16:19]
	v_mfma_f32_16x16x32_bf16 v[12:15], v[24:27], v[32:35], v[12:15]
	v_mfma_f32_16x16x32_bf16 v[4:7], v[152:155], v[32:35], v[4:7]
	v_mfma_f32_16x16x32_bf16 v[8:11], v[24:27], v[36:39], v[8:11]
	v_mfma_f32_16x16x32_bf16 v[20:23], v[152:155], v[36:39], v[20:23]
	global_load_dwordx4 v[28:31], v[148:149], off offset:448
	global_load_dwordx4 v[32:35], v[164:165], off offset:448
	global_load_dwordx4 v[36:39], v[170:171], off offset:448
	ds_read_b128 v[24:27], v182 offset:128
	ds_read_b128 v[152:155], v150 offset:128
	s_waitcnt vmcnt(18) lgkmcnt(2)
	v_mfma_f32_16x16x32_bf16 v[0:3], v[178:181], v[40:43], v[0:3]
	v_mfma_f32_16x16x32_bf16 v[16:19], v[246:249], v[40:43], v[16:19]
	v_mfma_f32_16x16x32_bf16 v[12:15], v[178:181], v[44:47], v[12:15]
	v_mfma_f32_16x16x32_bf16 v[4:7], v[246:249], v[44:47], v[4:7]
	v_mfma_f32_16x16x32_bf16 v[8:11], v[178:181], v[48:51], v[8:11]
	v_mfma_f32_16x16x32_bf16 v[20:23], v[246:249], v[48:51], v[20:23]
	ds_read_b128 v[178:181], v182 offset:192
	ds_read_b128 v[246:249], v150 offset:192
	s_waitcnt vmcnt(15) lgkmcnt(2)
	v_mfma_f32_16x16x32_bf16 v[0:3], v[24:27], v[136:139], v[0:3]
	v_mfma_f32_16x16x32_bf16 v[16:19], v[152:155], v[136:139], v[16:19]
	v_mfma_f32_16x16x32_bf16 v[12:15], v[24:27], v[140:143], v[12:15]
	v_mfma_f32_16x16x32_bf16 v[4:7], v[152:155], v[140:143], v[4:7]
	v_mfma_f32_16x16x32_bf16 v[8:11], v[24:27], v[144:147], v[8:11]
	v_mfma_f32_16x16x32_bf16 v[20:23], v[152:155], v[144:147], v[20:23]
	ds_read_b128 v[24:27], v182 offset:256
	ds_read_b128 v[152:155], v150 offset:256
	s_waitcnt vmcnt(12) lgkmcnt(2)
	v_mfma_f32_16x16x32_bf16 v[0:3], v[178:181], v[160:163], v[0:3]
	v_mfma_f32_16x16x32_bf16 v[16:19], v[246:249], v[160:163], v[16:19]
	v_mfma_f32_16x16x32_bf16 v[12:15], v[178:181], v[198:201], v[12:15]
	v_mfma_f32_16x16x32_bf16 v[4:7], v[246:249], v[198:201], v[4:7]
	v_mfma_f32_16x16x32_bf16 v[8:11], v[178:181], v[202:205], v[8:11]
	v_mfma_f32_16x16x32_bf16 v[20:23], v[246:249], v[202:205], v[20:23]
	ds_read_b128 v[178:181], v182 offset:320
	ds_read_b128 v[246:249], v150 offset:320
	s_waitcnt vmcnt(9) lgkmcnt(2)
	v_mfma_f32_16x16x32_bf16 v[0:3], v[24:27], v[206:209], v[0:3]
	v_mfma_f32_16x16x32_bf16 v[16:19], v[152:155], v[206:209], v[16:19]
	v_mfma_f32_16x16x32_bf16 v[12:15], v[24:27], v[210:213], v[12:15]
	v_mfma_f32_16x16x32_bf16 v[4:7], v[152:155], v[210:213], v[4:7]
	v_mfma_f32_16x16x32_bf16 v[8:11], v[24:27], v[214:217], v[8:11]
	v_mfma_f32_16x16x32_bf16 v[20:23], v[152:155], v[214:217], v[20:23]
	ds_read_b128 v[24:27], v182 offset:384
	ds_read_b128 v[152:155], v150 offset:384
	s_waitcnt vmcnt(6) lgkmcnt(2)
	v_mfma_f32_16x16x32_bf16 v[0:3], v[178:181], v[218:221], v[0:3]
	v_mfma_f32_16x16x32_bf16 v[16:19], v[246:249], v[218:221], v[16:19]
	v_mfma_f32_16x16x32_bf16 v[12:15], v[178:181], v[222:225], v[12:15]
	v_mfma_f32_16x16x32_bf16 v[4:7], v[246:249], v[222:225], v[4:7]
	v_mfma_f32_16x16x32_bf16 v[8:11], v[178:181], v[226:229], v[8:11]
	v_mfma_f32_16x16x32_bf16 v[20:23], v[246:249], v[226:229], v[20:23]
	ds_read_b128 v[178:181], v182 offset:448
	ds_read_b128 v[246:249], v150 offset:448
	s_waitcnt vmcnt(3) lgkmcnt(2)
	v_mfma_f32_16x16x32_bf16 v[0:3], v[24:27], v[230:233], v[0:3]
	v_mfma_f32_16x16x32_bf16 v[16:19], v[152:155], v[230:233], v[16:19]
	v_mfma_f32_16x16x32_bf16 v[12:15], v[24:27], v[234:237], v[12:15]
	v_mfma_f32_16x16x32_bf16 v[4:7], v[152:155], v[234:237], v[4:7]
	v_mfma_f32_16x16x32_bf16 v[8:11], v[24:27], v[238:241], v[8:11]
	v_mfma_f32_16x16x32_bf16 v[20:23], v[152:155], v[238:241], v[20:23]
	s_waitcnt vmcnt(0) lgkmcnt(0)
	v_mfma_f32_16x16x32_bf16 v[0:3], v[178:181], v[28:31], v[0:3]
	v_mfma_f32_16x16x32_bf16 v[16:19], v[246:249], v[28:31], v[16:19]
	v_mfma_f32_16x16x32_bf16 v[12:15], v[178:181], v[32:35], v[12:15]
	v_mfma_f32_16x16x32_bf16 v[4:7], v[246:249], v[32:35], v[4:7]
	v_mfma_f32_16x16x32_bf16 v[8:11], v[178:181], v[36:39], v[8:11]
	v_mfma_f32_16x16x32_bf16 v[20:23], v[246:249], v[36:39], v[20:23]
	s_nop 0
	s_barrier
	ds_write_b32 v193, v0
	ds_write_b32 v193, v1 offset:192
	ds_write_b32 v193, v2 offset:384
	ds_write_b32 v194, v3
	ds_write_b32 v193, v12 offset:64
	ds_write_b32 v193, v13 offset:256
	ds_write_b32 v193, v14 offset:448
	ds_write_b32 v194, v15 offset:64
	ds_write_b32 v193, v8 offset:128
	ds_write_b32 v193, v9 offset:320
	ds_write_b32 v193, v10 offset:512
	ds_write_b32 v194, v11 offset:128
	ds_write_b32 v193, v16 offset:3072
	ds_write_b32 v193, v17 offset:3264
	ds_write_b32 v193, v18 offset:3456
	ds_write_b32 v195, v19
	ds_write_b32 v193, v4 offset:3136
	ds_write_b32 v193, v5 offset:3328
	ds_write_b32 v193, v6 offset:3520
	ds_write_b32 v195, v7 offset:64
	ds_write_b32 v193, v20 offset:3200
	ds_write_b32 v193, v21 offset:3392
	ds_write_b32 v193, v22 offset:3584
	ds_write_b32 v195, v23 offset:128
	s_waitcnt lgkmcnt(0)
	s_barrier
	s_and_saveexec_b64 s[20:21], vcc
	s_cbranch_execz .LBB0_216
	s_lshl_b32 s4, s85, 5
	v_lshl_add_u32 v1, v108, 2, 0
	s_mov_b64 s[62:63], 0
	v_mov_b32_e32 v0, v108
	s_branch .LBB0_224
